# v020 with the GQA per-tile row-sum accumulated as a depth-6 tree of f32 adds instead of a 32-long dependent chain
# speedup vs baseline: 1.0095x; 1.0095x over previous
; #define SBAR() __builtin_amdgcn_sched_barrier(0)
; #define NAM(P0, P1, t) do { if constexpr (NA) na_mask(P0, P1, kr_lo + (t), r0, qrow, qc, c0, hi, bl); } while (0)
; #define PSM(P0, P1, MN, AL) do { if constexpr (NA) partialSM(P0, P1, m_reg, MN, AL); else { AL = 1.f; _Pragma("unroll") for (int r = 0; r < 16; ++r) P0[r] = __builtin_amdgcn_exp2f(P0[r]); } } while (0)
; #define RESCN(a) do { if constexpr (NA) RESC(a); } while (0)
; #define VM0() asm volatile("s_waitcnt vmcnt(0)" ::: "memory")
; #define NAM(P0, P1, t) do { if constexpr (NA) na_mask(P0, P1, kr_lo + (t), r0, qrow, qc, c0, hi, bl); } while (0)
; #define PSM(P0, P1, MN, AL) do { if constexpr (NA) partialSM(P0, P1, m_reg, MN, AL); else { AL = 1.f; _Pragma("unroll") for (int r = 0; r < 16; ++r) P0[r] = __builtin_amdgcn_exp2f(P0[r]); } } while (0)
; __device__ __forceinline__ void finishSM(f32x16& p0, f32x16& p1, float alpha, float& l_reg, bf16x8& pa0, bf16x8& pa1, bf16x8& pa2, bf16x8& pa3) {
;   for (int r = 0; r < 16; ++r) p1[r] = __builtin_amdgcn_exp2f(p1[r]);
;   float ps = 0; for (int r = 0; r < 16; ++r) ps += p0[r]; for (int r = 0; r < 16; ++r) ps += p1[r];
;   { auto rr = __builtin_amdgcn_permlane32_swap(__float_as_uint(ps), __float_as_uint(ps), false, false);
;     ps = __uint_as_float(rr[0]) + __uint_as_float(rr[1]); }
;   l_reg = l_reg * alpha + ps;
; template <bool NA, int ROWB>
; __device__ __forceinline__ void attn_dma(const bf16* __restrict__ Qb, const bf16* __restrict__ Kh, const bf16* __restrict__ Vh, bf16* __restrict__ Ob, int NT, char* lds, const int tid, float* __restrict__ ssb, int qrow0, int kr_lo, const float* bl) {
;     ...
;   for (int t = 1; t + 1 < NT; t += 2) {
;     DMA_TILE(t + 1, bn);
;     SBAR(); qkt<false>(pB0, pB1, (const bf16*)(K_lds + bc * SHM_K), qr, nullptr, r32, hi); NAM(pB0, pB1, t);
;     finishSM(pA0, pA1, alA, l_reg, pa0, pa1, pa2, pa3); SBAR();
;     pv_d0(o, vb0 + bp * (int)SHM_V, pa0, pa1, pa2, pa3); PSM(pB0, pB1, mnB, alB); RESCN(alB);
;     VM0(); __syncthreads();
;     bp = bc; bc = bn; bn = NEXTB(bn);
;     if (t + 2 < NT) DMA_TILE(t + 2, bn);
;     SBAR(); qkt<false>(pA0, pA1, (const bf16*)(K_lds + bc * SHM_K), qr, nullptr, r32, hi); NAM(pA0, pA1, t + 1);
;     finishSM(pB0, pB1, alB, l_reg, pa0, pa1, pa2, pa3); SBAR();
;     pv_d0(o, vb0 + bp * (int)SHM_V, pa0, pa1, pa2, pa3); PSM(pA0, pA1, mnA, alA); RESCN(alA);
.Lgqa_lead:
	v_mov_b32_e32 v80, v212
	v_mov_b32_e32 v81, v214
	v_mov_b32_e32 v82, v210
	v_mov_b32_e32 v83, v213
	v_mov_b32_e32 v84, v208
	v_mov_b32_e32 v85, v211
	v_mov_b32_e32 v86, v207
	v_mov_b32_e32 v87, v209
	v_mov_b32_e32 v88, v203
	v_mov_b32_e32 v89, v206
	v_mov_b32_e32 v90, v198
	v_mov_b32_e32 v91, v205
	v_mov_b32_e32 v92, v196
	v_mov_b32_e32 v93, v199
	v_mov_b32_e32 v94, v175
	v_mov_b32_e32 v95, v197
	v_add_u32_e32 v215, s24, v195
	ds_read_b64_tr_b16 v[146:147], v215 offset:0
	ds_read_b64_tr_b16 v[148:149], v215 offset:2048
	ds_read_b64_tr_b16 v[150:151], v215 offset:4096
	ds_read_b64_tr_b16 v[152:153], v215 offset:6144
	ds_read_b64_tr_b16 v[154:155], v215 offset:8192
	ds_read_b64_tr_b16 v[156:157], v215 offset:10240
	ds_read_b64_tr_b16 v[158:159], v215 offset:12288
	ds_read_b64_tr_b16 v[160:161], v215 offset:14336
	ds_read_b64_tr_b16 v[176:177], v215 offset:512
	ds_read_b64_tr_b16 v[178:179], v215 offset:2560
	ds_read_b64_tr_b16 v[180:181], v215 offset:4608
	ds_read_b64_tr_b16 v[182:183], v215 offset:6656
	ds_read_b64_tr_b16 v[216:217], v215 offset:8704
	ds_read_b64_tr_b16 v[218:219], v215 offset:10752
	ds_read_b64_tr_b16 v[220:221], v215 offset:12800
	ds_read_b64_tr_b16 v[222:223], v215 offset:14848
	ds_read_b64_tr_b16 v[224:225], v215 offset:1024
	ds_read_b64_tr_b16 v[226:227], v215 offset:3072
	ds_read_b64_tr_b16 v[234:235], v215 offset:5120
	ds_read_b64_tr_b16 v[236:237], v215 offset:7168
	ds_read_b64_tr_b16 v[240:241], v215 offset:9216
	ds_read_b64_tr_b16 v[242:243], v215 offset:11264
	ds_read_b64_tr_b16 v[244:245], v215 offset:13312
	ds_read_b64_tr_b16 v[246:247], v215 offset:15360
	ds_read_b64_tr_b16 v[248:249], v215 offset:1536
	ds_read_b64_tr_b16 v[250:251], v215 offset:3584
	ds_read_b64_tr_b16 v[196:197], v215 offset:5632
	ds_read_b64_tr_b16 v[198:199], v215 offset:7680
	ds_read_b64_tr_b16 v[206:207], v215 offset:9728
	ds_read_b64_tr_b16 v[208:209], v215 offset:11776
	ds_read_b64_tr_b16 v[210:211], v215 offset:13824
	ds_read_b64_tr_b16 v[212:213], v215 offset:15872
	v_add_u32_e32 v229, s0, v187
	v_add_u32_e32 v230, s0, v188
	v_add_u32_e32 v232, s0, v189
	v_add_u32_e32 v238, s0, v190
	v_add_u32_e32 v203, s0, v191
	v_add_u32_e32 v205, s0, v192
	v_add_u32_e32 v214, s0, v193
	v_add_u32_e32 v175, s0, v194
	v_exp_f32_e32 v64, v64
	v_exp_f32_e32 v65, v65
	v_exp_f32_e32 v66, v66
	v_exp_f32_e32 v67, v67
	v_exp_f32_e32 v68, v68
	v_exp_f32_e32 v69, v69
	v_exp_f32_e32 v70, v70
	v_exp_f32_e32 v71, v71
	v_exp_f32_e32 v72, v72
	v_exp_f32_e32 v73, v73
	v_exp_f32_e32 v74, v74
	v_exp_f32_e32 v75, v75
	v_exp_f32_e32 v76, v76
	v_exp_f32_e32 v77, v77
	v_exp_f32_e32 v78, v78
	v_exp_f32_e32 v79, v79
	v_cvt_pk_bf16_f32 v96, v80, v81
	v_cvt_pk_bf16_f32 v97, v82, v83
	v_cvt_pk_bf16_f32 v98, v84, v85
	v_cvt_pk_bf16_f32 v99, v86, v87
	v_cvt_pk_bf16_f32 v100, v88, v89
	v_cvt_pk_bf16_f32 v101, v90, v91
	v_cvt_pk_bf16_f32 v102, v92, v93
	v_cvt_pk_bf16_f32 v103, v94, v95
	v_cvt_pk_bf16_f32 v104, v64, v65
	v_cvt_pk_bf16_f32 v105, v66, v67
	v_cvt_pk_bf16_f32 v106, v68, v69
	v_cvt_pk_bf16_f32 v107, v70, v71
	v_cvt_pk_bf16_f32 v108, v72, v73
	v_cvt_pk_bf16_f32 v109, v74, v75
	v_cvt_pk_bf16_f32 v110, v76, v77
	v_cvt_pk_bf16_f32 v111, v78, v79
	s_add_u32 s98, s40, s18
	s_addc_u32 s99, s41, 0
	s_add_i32 s25, s17, s4
	s_add_i32 m0, s25, 0xc000
	s_nop 0
	global_load_lds_dwordx4 v164, s[98:99]
	s_add_i32 m0, s25, 0xc400
	s_nop 0
	global_load_lds_dwordx4 v168, s[98:99]
	s_waitcnt lgkmcnt(0)
	s_barrier
	s_setprio 1
	v_mfma_f32_32x32x16_bf16 v[0:15], v[96:99], v[146:149], v[0:15]
	ds_read_b128 v[146:149], v229 offset:49152
	v_mfma_f32_32x32x16_bf16 v[0:15], v[100:103], v[150:153], v[0:15]
	ds_read_b128 v[150:153], v229 offset:57344
	v_mfma_f32_32x32x16_bf16 v[0:15], v[104:107], v[154:157], v[0:15]
	ds_read_b128 v[154:157], v230 offset:49152
	v_mfma_f32_32x32x16_bf16 v[0:15], v[108:111], v[158:161], v[0:15]
	ds_read_b128 v[158:161], v230 offset:57344
	v_mfma_f32_32x32x16_bf16 v[16:31], v[96:99], v[176:179], v[16:31]
	ds_read_b128 v[176:179], v232 offset:49152
	v_mfma_f32_32x32x16_bf16 v[16:31], v[100:103], v[180:183], v[16:31]
	ds_read_b128 v[180:183], v232 offset:57344
	v_mfma_f32_32x32x16_bf16 v[16:31], v[104:107], v[216:219], v[16:31]
	ds_read_b128 v[216:219], v238 offset:49152
	v_mfma_f32_32x32x16_bf16 v[16:31], v[108:111], v[220:223], v[16:31]
	ds_read_b128 v[220:223], v238 offset:57344
	v_mfma_f32_32x32x16_bf16 v[32:47], v[96:99], v[224:227], v[32:47]
	ds_read_b128 v[224:227], v203 offset:49152
	v_mfma_f32_32x32x16_bf16 v[32:47], v[100:103], v[234:237], v[32:47]
	ds_read_b128 v[234:237], v203 offset:57344
	v_mfma_f32_32x32x16_bf16 v[32:47], v[104:107], v[240:243], v[32:47]
	ds_read_b128 v[240:243], v205 offset:49152
	v_mfma_f32_32x32x16_bf16 v[32:47], v[108:111], v[244:247], v[32:47]
	ds_read_b128 v[244:247], v205 offset:57344
	v_mfma_f32_32x32x16_bf16 v[48:63], v[96:99], v[248:251], v[48:63]
	ds_read_b128 v[248:251], v214 offset:49152
	v_mfma_f32_32x32x16_bf16 v[48:63], v[100:103], v[196:199], v[48:63]
	ds_read_b128 v[196:199], v214 offset:57344
	v_mfma_f32_32x32x16_bf16 v[48:63], v[104:107], v[206:209], v[48:63]
	ds_read_b128 v[206:209], v175 offset:49152
	v_mfma_f32_32x32x16_bf16 v[48:63], v[108:111], v[210:213], v[48:63]
	ds_read_b128 v[210:213], v175 offset:57344
	s_setprio 0
	s_waitcnt vmcnt(0)
	s_barrier
	v_add_f32_e32 v80, v80, v64
	v_add_f32_e32 v81, v81, v65
	v_add_f32_e32 v82, v82, v66
	v_add_f32_e32 v83, v83, v67
	v_add_f32_e32 v84, v84, v68
	v_add_f32_e32 v85, v85, v69
	v_add_f32_e32 v86, v86, v70
	v_add_f32_e32 v87, v87, v71
	v_add_f32_e32 v88, v88, v72
	v_add_f32_e32 v89, v89, v73
	v_add_f32_e32 v90, v90, v74
	v_add_f32_e32 v91, v91, v75
	v_add_f32_e32 v92, v92, v76
	v_add_f32_e32 v93, v93, v77
	v_add_f32_e32 v94, v94, v78
	v_add_f32_e32 v95, v95, v79
	v_add_f32_e32 v80, v80, v88
	v_add_f32_e32 v81, v81, v89
	v_add_f32_e32 v82, v82, v90
	v_add_f32_e32 v83, v83, v91
	v_add_f32_e32 v84, v84, v92
	v_add_f32_e32 v85, v85, v93
	v_add_f32_e32 v86, v86, v94
	v_add_f32_e32 v87, v87, v95
	v_add_f32_e32 v80, v80, v84
	v_add_f32_e32 v81, v81, v85
	v_add_f32_e32 v82, v82, v86
	v_add_f32_e32 v83, v83, v87
	v_add_f32_e32 v80, v80, v82
	v_add_f32_e32 v81, v81, v83
	v_add_f32_e32 v80, v80, v81
	v_add_f32_e32 v112, v80, v112
	s_add_u32 s100, s42, s18
	s_addc_u32 s101, s43, 0
	s_add_i32 s18, s18, 0x4000
	s_and_b32 s18, s18, 0x1fffff
	s_add_u32 s98, s40, s18
	s_addc_u32 s99, s41, 0
	s_add_i32 s1, s24, s4
	s_add_i32 s25, s17, s4
	s_add_i32 m0, s1, 0xc000
	s_nop 0
	global_load_lds_dwordx4 v164, s[98:99]
	s_mov_b32 m0, s25
	s_nop 0
	global_load_lds_dwordx4 v166, s[100:101]
	s_add_i32 m0, s1, 0xc400
	s_nop 0
	global_load_lds_dwordx4 v168, s[98:99]
	s_add_i32 m0, s25, 0x400
	s_nop 0
	global_load_lds_dwordx4 v170, s[100:101]
	s_mov_b32 s1, s24
	s_mov_b32 s24, s0
	s_mov_b32 s0, s17
	s_mov_b32 s17, s1
	v_add_u32_e32 v215, s24, v195
	s_waitcnt lgkmcnt(0)
	s_barrier
; #define SBAR() __builtin_amdgcn_sched_barrier(0)
; #define NAM(P0, P1, t) do { if constexpr (NA) na_mask(P0, P1, kr_lo + (t), r0, qrow, qc, c0, hi, bl); } while (0)
; #define PSM(P0, P1, MN, AL) do { if constexpr (NA) partialSM(P0, P1, m_reg, MN, AL); else { AL = 1.f; _Pragma("unroll") for (int r = 0; r < 16; ++r) P0[r] = __builtin_amdgcn_exp2f(P0[r]); } } while (0)
; #define RESCN(a) do { if constexpr (NA) RESC(a); } while (0)
; #define VM0() asm volatile("s_waitcnt vmcnt(0)" ::: "memory")
; #define NAM(P0, P1, t) do { if constexpr (NA) na_mask(P0, P1, kr_lo + (t), r0, qrow, qc, c0, hi, bl); } while (0)
; #define RESCN(a) do { if constexpr (NA) RESC(a); } while (0)
; template <bool QL>
; __device__ __forceinline__ void qkt(f32x16& p0, f32x16& p1, const bf16* Ks, const bf16x8* qr, const char* ql, int r32, int hi) {
;   p0 = f32x16{}; p1 = f32x16{};
;   for (int d0 = 0; d0 < 8; ++d0) { int cb = (d0 * 16 + hi * 8) * 2;
;     bf16x8 b0 = *reinterpret_cast<const bf16x8*>((const char*)Ks + KSWZ(r32, cb));
;     bf16x8 b1 = *reinterpret_cast<const bf16x8*>((const char*)Ks + KSWZ(32 + r32, cb));
;     bf16x8 q; if constexpr (QL) q = *reinterpret_cast<const bf16x8*>(ql + d0 * 1024); else q = qr[d0];
;     p0 = __builtin_amdgcn_mfma_f32_32x32x16_bf16(b0, q, p0, 0, 0, 0);
;     p1 = __builtin_amdgcn_mfma_f32_32x32x16_bf16(b1, q, p1, 0, 0, 0); }
; template <bool NA, int ROWB>
; __device__ __forceinline__ void attn_dma(const bf16* __restrict__ Qb, const bf16* __restrict__ Kh, const bf16* __restrict__ Vh, bf16* __restrict__ Ob, int NT, char* lds, const int tid, float* __restrict__ ssb, int qrow0, int kr_lo, const float* bl) {
;     ...
;   for (int t = 1; t + 1 < NT; t += 2) {
;     DMA_TILE(t + 1, bn);
;     SBAR(); qkt<false>(pB0, pB1, (const bf16*)(K_lds + bc * SHM_K), qr, nullptr, r32, hi); NAM(pB0, pB1, t);
;     finishSM(pA0, pA1, alA, l_reg, pa0, pa1, pa2, pa3); SBAR();
;     pv_d0(o, vb0 + bp * (int)SHM_V, pa0, pa1, pa2, pa3); PSM(pB0, pB1, mnB, alB); RESCN(alB);
;     VM0(); __syncthreads();
;     bp = bc; bc = bn; bn = NEXTB(bn);
;     if (t + 2 < NT) DMA_TILE(t + 2, bn);
;     SBAR(); qkt<false>(pA0, pA1, (const bf16*)(K_lds + bc * SHM_K), qr, nullptr, r32, hi); NAM(pA0, pA1, t + 1);
;     finishSM(pB0, pB1, alB, l_reg, pa0, pa1, pa2, pa3); SBAR();
;     pv_d0(o, vb0 + bp * (int)SHM_V, pa0, pa1, pa2, pa3); PSM(pA0, pA1, mnA, alA); RESCN(alA);
.Lgqa_loop:
	s_setprio 1
	v_mfma_f32_32x32x16_bf16 v[80:95], v[146:149], v[138:141], 0
	ds_read_b64_tr_b16 v[146:147], v215 offset:0
	ds_read_b64_tr_b16 v[148:149], v215 offset:2048
	v_mfma_f32_32x32x16_bf16 v[64:79], v[150:153], v[138:141], 0
	ds_read_b64_tr_b16 v[150:151], v215 offset:4096
	ds_read_b64_tr_b16 v[152:153], v215 offset:6144
	v_mfma_f32_32x32x16_bf16 v[80:95], v[154:157], v[142:145], v[80:95]
	ds_read_b64_tr_b16 v[154:155], v215 offset:8192
	ds_read_b64_tr_b16 v[156:157], v215 offset:10240
	v_mfma_f32_32x32x16_bf16 v[64:79], v[158:161], v[142:145], v[64:79]
	ds_read_b64_tr_b16 v[158:159], v215 offset:12288
	ds_read_b64_tr_b16 v[160:161], v215 offset:14336
	v_mfma_f32_32x32x16_bf16 v[80:95], v[176:179], v[134:137], v[80:95]
	ds_read_b64_tr_b16 v[176:177], v215 offset:512
	ds_read_b64_tr_b16 v[178:179], v215 offset:2560
	v_mfma_f32_32x32x16_bf16 v[64:79], v[180:183], v[134:137], v[64:79]
	ds_read_b64_tr_b16 v[180:181], v215 offset:4608
	ds_read_b64_tr_b16 v[182:183], v215 offset:6656
	v_mfma_f32_32x32x16_bf16 v[80:95], v[216:219], v[114:117], v[80:95]
	ds_read_b64_tr_b16 v[216:217], v215 offset:8704
	ds_read_b64_tr_b16 v[218:219], v215 offset:10752
	v_mfma_f32_32x32x16_bf16 v[64:79], v[220:223], v[114:117], v[64:79]
	ds_read_b64_tr_b16 v[220:221], v215 offset:12800
	ds_read_b64_tr_b16 v[222:223], v215 offset:14848
	v_mfma_f32_32x32x16_bf16 v[80:95], v[224:227], v[118:121], v[80:95]
	ds_read_b64_tr_b16 v[224:225], v215 offset:1024
	ds_read_b64_tr_b16 v[226:227], v215 offset:3072
	v_mfma_f32_32x32x16_bf16 v[64:79], v[234:237], v[118:121], v[64:79]
	ds_read_b64_tr_b16 v[234:235], v215 offset:5120
	ds_read_b64_tr_b16 v[236:237], v215 offset:7168
	v_mfma_f32_32x32x16_bf16 v[80:95], v[240:243], v[122:125], v[80:95]
	ds_read_b64_tr_b16 v[240:241], v215 offset:9216
	ds_read_b64_tr_b16 v[242:243], v215 offset:11264
	v_mfma_f32_32x32x16_bf16 v[64:79], v[244:247], v[122:125], v[64:79]
	ds_read_b64_tr_b16 v[244:245], v215 offset:13312
	ds_read_b64_tr_b16 v[246:247], v215 offset:15360
	v_mfma_f32_32x32x16_bf16 v[80:95], v[248:251], v[126:129], v[80:95]
	ds_read_b64_tr_b16 v[248:249], v215 offset:1536
	ds_read_b64_tr_b16 v[250:251], v215 offset:3584
	v_mfma_f32_32x32x16_bf16 v[64:79], v[196:199], v[126:129], v[64:79]
	ds_read_b64_tr_b16 v[196:197], v215 offset:5632
	ds_read_b64_tr_b16 v[198:199], v215 offset:7680
	v_mfma_f32_32x32x16_bf16 v[80:95], v[206:209], v[130:133], v[80:95]
	ds_read_b64_tr_b16 v[206:207], v215 offset:9728
	ds_read_b64_tr_b16 v[208:209], v215 offset:11776
	v_mfma_f32_32x32x16_bf16 v[64:79], v[210:213], v[130:133], v[64:79]
	ds_read_b64_tr_b16 v[210:211], v215 offset:13824
	ds_read_b64_tr_b16 v[212:213], v215 offset:15872
	s_setprio 0
	s_barrier
	s_nop 7
	v_exp_f32_e32 v80, v80
	v_exp_f32_e32 v81, v81
	v_exp_f32_e32 v82, v82
	v_exp_f32_e32 v83, v83
	v_exp_f32_e32 v84, v84
	v_exp_f32_e32 v85, v85
	v_exp_f32_e32 v86, v86
	v_exp_f32_e32 v87, v87
	v_exp_f32_e32 v88, v88
	v_exp_f32_e32 v89, v89
	v_exp_f32_e32 v90, v90
	v_exp_f32_e32 v91, v91
	v_exp_f32_e32 v92, v92
	v_exp_f32_e32 v93, v93
	v_exp_f32_e32 v94, v94
	v_exp_f32_e32 v95, v95
	v_add_u32_e32 v229, s0, v187
	v_add_u32_e32 v230, s0, v188
	v_add_u32_e32 v232, s0, v189
	v_add_u32_e32 v238, s0, v190
	v_add_u32_e32 v203, s0, v191
	v_add_u32_e32 v205, s0, v192
	v_add_u32_e32 v214, s0, v193
	v_add_u32_e32 v175, s0, v194
	v_exp_f32_e32 v64, v64
	v_exp_f32_e32 v65, v65
	v_exp_f32_e32 v66, v66
	v_exp_f32_e32 v67, v67
	v_exp_f32_e32 v68, v68
	v_exp_f32_e32 v69, v69
	v_exp_f32_e32 v70, v70
	v_exp_f32_e32 v71, v71
	v_exp_f32_e32 v72, v72
	v_exp_f32_e32 v73, v73
	v_exp_f32_e32 v74, v74
	v_exp_f32_e32 v75, v75
	v_exp_f32_e32 v76, v76
	v_exp_f32_e32 v77, v77
	v_exp_f32_e32 v78, v78
	v_exp_f32_e32 v79, v79
	v_cvt_pk_bf16_f32 v96, v80, v81
	v_cvt_pk_bf16_f32 v97, v82, v83
	v_cvt_pk_bf16_f32 v98, v84, v85
	v_cvt_pk_bf16_f32 v99, v86, v87
	v_cvt_pk_bf16_f32 v100, v88, v89
	v_cvt_pk_bf16_f32 v101, v90, v91
	v_cvt_pk_bf16_f32 v102, v92, v93
	v_cvt_pk_bf16_f32 v103, v94, v95
	v_cvt_pk_bf16_f32 v104, v64, v65
	v_cvt_pk_bf16_f32 v105, v66, v67
	v_cvt_pk_bf16_f32 v106, v68, v69
	v_cvt_pk_bf16_f32 v107, v70, v71
	v_cvt_pk_bf16_f32 v108, v72, v73
	v_cvt_pk_bf16_f32 v109, v74, v75
	v_cvt_pk_bf16_f32 v110, v76, v77
	v_cvt_pk_bf16_f32 v111, v78, v79
	s_waitcnt lgkmcnt(0)
	s_barrier
; #define SBAR() __builtin_amdgcn_sched_barrier(0)
; #define NAM(P0, P1, t) do { if constexpr (NA) na_mask(P0, P1, kr_lo + (t), r0, qrow, qc, c0, hi, bl); } while (0)
; #define PSM(P0, P1, MN, AL) do { if constexpr (NA) partialSM(P0, P1, m_reg, MN, AL); else { AL = 1.f; _Pragma("unroll") for (int r = 0; r < 16; ++r) P0[r] = __builtin_amdgcn_exp2f(P0[r]); } } while (0)
; #define RESCN(a) do { if constexpr (NA) RESC(a); } while (0)
; #define VM0() asm volatile("s_waitcnt vmcnt(0)" ::: "memory")
; #define NAM(P0, P1, t) do { if constexpr (NA) na_mask(P0, P1, kr_lo + (t), r0, qrow, qc, c0, hi, bl); } while (0)
; #define PSM(P0, P1, MN, AL) do { if constexpr (NA) partialSM(P0, P1, m_reg, MN, AL); else { AL = 1.f; _Pragma("unroll") for (int r = 0; r < 16; ++r) P0[r] = __builtin_amdgcn_exp2f(P0[r]); } } while (0)
; #define RESCN(a) do { if constexpr (NA) RESC(a); } while (0)
; template <bool NA, int ROWB>
; __device__ __forceinline__ void attn_dma(const bf16* __restrict__ Qb, const bf16* __restrict__ Kh, const bf16* __restrict__ Vh, bf16* __restrict__ Ob, int NT, char* lds, const int tid, float* __restrict__ ssb, int qrow0, int kr_lo, const float* bl) {
;     ...
;   for (int t = 1; t + 1 < NT; t += 2) {
;     DMA_TILE(t + 1, bn);
;     SBAR(); qkt<false>(pB0, pB1, (const bf16*)(K_lds + bc * SHM_K), qr, nullptr, r32, hi); NAM(pB0, pB1, t);
;     finishSM(pA0, pA1, alA, l_reg, pa0, pa1, pa2, pa3); SBAR();
;     pv_d0(o, vb0 + bp * (int)SHM_V, pa0, pa1, pa2, pa3); PSM(pB0, pB1, mnB, alB); RESCN(alB);
;     VM0(); __syncthreads();
;     bp = bc; bc = bn; bn = NEXTB(bn);
;     if (t + 2 < NT) DMA_TILE(t + 2, bn);
;     SBAR(); qkt<false>(pA0, pA1, (const bf16*)(K_lds + bc * SHM_K), qr, nullptr, r32, hi); NAM(pA0, pA1, t + 1);
;     finishSM(pB0, pB1, alB, l_reg, pa0, pa1, pa2, pa3); SBAR();
;     pv_d0(o, vb0 + bp * (int)SHM_V, pa0, pa1, pa2, pa3); PSM(pA0, pA1, mnA, alA); RESCN(alA);
;     VM0(); __syncthreads();
;     bp = bc; bc = bn; bn = NEXTB(bn);
;   }
;   SBAR(); qkt<false>(pB0, pB1, (const bf16*)(K_lds + bc * SHM_K), qr, nullptr, r32, hi); NAM(pB0, pB1, NT - 1);
	s_setprio 1
	v_mfma_f32_32x32x16_bf16 v[0:15], v[96:99], v[146:149], v[0:15]
	ds_read_b128 v[146:149], v229 offset:49152
	v_mfma_f32_32x32x16_bf16 v[0:15], v[100:103], v[150:153], v[0:15]
	ds_read_b128 v[150:153], v229 offset:57344
	v_mfma_f32_32x32x16_bf16 v[0:15], v[104:107], v[154:157], v[0:15]
	ds_read_b128 v[154:157], v230 offset:49152
	v_mfma_f32_32x32x16_bf16 v[0:15], v[108:111], v[158:161], v[0:15]
	ds_read_b128 v[158:161], v230 offset:57344
	v_mfma_f32_32x32x16_bf16 v[16:31], v[96:99], v[176:179], v[16:31]
	ds_read_b128 v[176:179], v232 offset:49152
	v_mfma_f32_32x32x16_bf16 v[16:31], v[100:103], v[180:183], v[16:31]
	ds_read_b128 v[180:183], v232 offset:57344
	v_mfma_f32_32x32x16_bf16 v[16:31], v[104:107], v[216:219], v[16:31]
	ds_read_b128 v[216:219], v238 offset:49152
	v_mfma_f32_32x32x16_bf16 v[16:31], v[108:111], v[220:223], v[16:31]
	ds_read_b128 v[220:223], v238 offset:57344
	v_mfma_f32_32x32x16_bf16 v[32:47], v[96:99], v[224:227], v[32:47]
	ds_read_b128 v[224:227], v203 offset:49152
	v_mfma_f32_32x32x16_bf16 v[32:47], v[100:103], v[234:237], v[32:47]
	ds_read_b128 v[234:237], v203 offset:57344
	v_mfma_f32_32x32x16_bf16 v[32:47], v[104:107], v[240:243], v[32:47]
	ds_read_b128 v[240:243], v205 offset:49152
	v_mfma_f32_32x32x16_bf16 v[32:47], v[108:111], v[244:247], v[32:47]
	ds_read_b128 v[244:247], v205 offset:57344
	v_mfma_f32_32x32x16_bf16 v[48:63], v[96:99], v[248:251], v[48:63]
	ds_read_b128 v[248:251], v214 offset:49152
	v_mfma_f32_32x32x16_bf16 v[48:63], v[100:103], v[196:199], v[48:63]
	ds_read_b128 v[196:199], v214 offset:57344
	v_mfma_f32_32x32x16_bf16 v[48:63], v[104:107], v[206:209], v[48:63]
	ds_read_b128 v[206:209], v175 offset:49152
	v_mfma_f32_32x32x16_bf16 v[48:63], v[108:111], v[210:213], v[48:63]
	ds_read_b128 v[210:213], v175 offset:57344
	s_setprio 0
	s_waitcnt vmcnt(0)
	s_barrier
	v_add_f32_e32 v80, v80, v64
	v_add_f32_e32 v81, v81, v65
	v_add_f32_e32 v82, v82, v66
	v_add_f32_e32 v83, v83, v67
	v_add_f32_e32 v84, v84, v68
	v_add_f32_e32 v85, v85, v69
	v_add_f32_e32 v86, v86, v70
	v_add_f32_e32 v87, v87, v71
	v_add_f32_e32 v88, v88, v72
	v_add_f32_e32 v89, v89, v73
	v_add_f32_e32 v90, v90, v74
	v_add_f32_e32 v91, v91, v75
	v_add_f32_e32 v92, v92, v76
	v_add_f32_e32 v93, v93, v77
	v_add_f32_e32 v94, v94, v78
	v_add_f32_e32 v95, v95, v79
	v_add_f32_e32 v80, v80, v88
	v_add_f32_e32 v81, v81, v89
	v_add_f32_e32 v82, v82, v90
	v_add_f32_e32 v83, v83, v91
	v_add_f32_e32 v84, v84, v92
	v_add_f32_e32 v85, v85, v93
	v_add_f32_e32 v86, v86, v94
	v_add_f32_e32 v87, v87, v95
	v_add_f32_e32 v80, v80, v84
	v_add_f32_e32 v81, v81, v85
	v_add_f32_e32 v82, v82, v86
	v_add_f32_e32 v83, v83, v87
	v_add_f32_e32 v80, v80, v82
	v_add_f32_e32 v81, v81, v83
	v_add_f32_e32 v80, v80, v81
	v_add_f32_e32 v112, v80, v112
	s_add_u32 s100, s42, s18
	s_addc_u32 s101, s43, 0
	s_add_i32 s18, s18, 0x4000
	s_and_b32 s18, s18, 0x1fffff
	s_add_u32 s98, s40, s18
	s_addc_u32 s99, s41, 0
	s_add_i32 s1, s24, s4
	s_add_i32 s25, s17, s4
	s_add_i32 m0, s1, 0xc000
	s_nop 0
	global_load_lds_dwordx4 v164, s[98:99]
	s_mov_b32 m0, s25
	s_nop 0
	global_load_lds_dwordx4 v166, s[100:101]
	s_add_i32 m0, s1, 0xc400
	s_nop 0
	global_load_lds_dwordx4 v168, s[98:99]
	s_add_i32 m0, s25, 0x400
	s_nop 0
	global_load_lds_dwordx4 v170, s[100:101]
	s_mov_b32 s1, s24
	s_mov_b32 s24, s0
	s_mov_b32 s0, s17
	s_mov_b32 s17, s1
	v_add_u32_e32 v215, s24, v195
	s_waitcnt lgkmcnt(0)
	s_barrier
	s_add_i32 s16, s16, 1
	s_cmp_eq_u32 s16, 125
	s_cbranch_scc0 .Lgqa_loop
	s_setprio 1
	v_mfma_f32_32x32x16_bf16 v[80:95], v[146:149], v[138:141], 0
	v_mfma_f32_32x32x16_bf16 v[64:79], v[150:153], v[138:141], 0
	v_mfma_f32_32x32x16_bf16 v[80:95], v[154:157], v[142:145], v[80:95]
	v_mfma_f32_32x32x16_bf16 v[64:79], v[158:161], v[142:145], v[64:79]
	v_mfma_f32_32x32x16_bf16 v[80:95], v[176:179], v[134:137], v[80:95]
	v_mfma_f32_32x32x16_bf16 v[64:79], v[180:183], v[134:137], v[64:79]
	v_mfma_f32_32x32x16_bf16 v[80:95], v[216:219], v[114:117], v[80:95]
	v_mfma_f32_32x32x16_bf16 v[64:79], v[220:223], v[114:117], v[64:79]
	v_mfma_f32_32x32x16_bf16 v[80:95], v[224:227], v[118:121], v[80:95]
	v_mfma_f32_32x32x16_bf16 v[64:79], v[234:237], v[118:121], v[64:79]
	v_mfma_f32_32x32x16_bf16 v[80:95], v[240:243], v[122:125], v[80:95]
	v_mfma_f32_32x32x16_bf16 v[64:79], v[244:247], v[122:125], v[64:79]
	v_mfma_f32_32x32x16_bf16 v[80:95], v[248:251], v[126:129], v[80:95]
	v_mfma_f32_32x32x16_bf16 v[64:79], v[196:199], v[126:129], v[64:79]
	v_mfma_f32_32x32x16_bf16 v[80:95], v[206:209], v[130:133], v[80:95]
	v_mfma_f32_32x32x16_bf16 v[64:79], v[210:213], v[130:133], v[64:79]
	s_setprio 0
	s_waitcnt vmcnt(0)
	s_barrier
	s_cmp_ge_u32 s4, 0x2000
	s_cbranch_scc1 .Lgqa_trail
	s_barrier
